# P3 attention: K-tile LDS writes issued before the first barrier of each half-iteration (their buffer is already free); only the V writes remain between the barriers
# baseline (speedup 1.0000x reference)
.LBB0_433:
	ds_read_b128 v[64:67], v166 offset:49152
	ds_read_b128 v[68:71], v166 offset:57344
	ds_read_b128 v[176:179], v167 offset:49152
	ds_read_b128 v[198:201], v167 offset:57344
	ds_read_b128 v[202:205], v168 offset:49152
	ds_read_b128 v[210:213], v168 offset:57344
	v_exp_f32_e32 v142, v142
	v_exp_f32_e32 v143, v143
	s_waitcnt lgkmcnt(5)
	v_mfma_f32_32x32x16_bf16 v[80:95], v[64:67], v[124:127], 0
	v_exp_f32_e32 v180, v140
	v_exp_f32_e32 v181, v141
	v_exp_f32_e32 v206, v138
	v_exp_f32_e32 v207, v135
	v_exp_f32_e32 v148, v148
	v_exp_f32_e32 v149, v149
	v_exp_f32_e32 v209, v146
	s_waitcnt lgkmcnt(4)
	v_mfma_f32_32x32x16_bf16 v[64:79], v[68:71], v[124:127], 0
	v_cvt_pk_bf16_f32 v135, v192, v193
	v_cvt_pk_bf16_f32 v138, v182, v183
	v_cvt_pk_bf16_f32 v140, v185, v187
	v_cvt_pk_bf16_f32 v141, v188, v189
	s_nop 0
	s_waitcnt lgkmcnt(3)
	v_mfma_f32_32x32x16_bf16 v[80:95], v[176:179], v[120:123], v[80:95]
	ds_read_b128 v[176:179], v169 offset:49152
	ds_read_b128 v[214:217], v169 offset:57344
	ds_read_b128 v[218:221], v170 offset:49152
	ds_read_b128 v[222:225], v170 offset:57344
	ds_read_b128 v[226:229], v171 offset:49152
	ds_read_b128 v[230:233], v171 offset:57344
	ds_read_b128 v[234:237], v172 offset:49152
	ds_read_b128 v[238:241], v172 offset:57344
	s_waitcnt lgkmcnt(10)
	v_mfma_f32_32x32x16_bf16 v[64:79], v[198:201], v[120:123], v[64:79]
	ds_read_b128 v[198:201], v173 offset:49152
	ds_read_b128 v[242:245], v173 offset:57344
	s_waitcnt lgkmcnt(11)
	v_mfma_f32_32x32x16_bf16 v[80:95], v[202:205], v[112:115], v[80:95]
	v_exp_f32_e32 v205, v134
	v_add_f32_e32 v134, v191, v190
	v_add_f32_e32 v134, v192, v134
	v_add_f32_e32 v134, v193, v134
	v_add_f32_e32 v134, v194, v134
	v_add_f32_e32 v134, v196, v134
	s_waitcnt lgkmcnt(10)
	v_mfma_f32_32x32x16_bf16 v[64:79], v[210:213], v[112:115], v[64:79]
	v_add_f32_e32 v134, v195, v134
	v_add_f32_e32 v134, v197, v134
	v_add_f32_e32 v134, v182, v134
	v_add_f32_e32 v134, v183, v134
	v_add_f32_e32 v134, v184, v134
	v_add_f32_e32 v134, v186, v134
	v_add_f32_e32 v134, v185, v134
	s_waitcnt lgkmcnt(9)
	v_mfma_f32_32x32x16_bf16 v[80:95], v[176:179], v[116:119], v[80:95]
	v_add_f32_e32 v134, v187, v134
	v_add_f32_e32 v134, v188, v134
	v_add_f32_e32 v134, v189, v134
	v_add_f32_e32 v134, v142, v134
	v_exp_f32_e32 v202, v139
	v_add_f32_e32 v134, v143, v134
	v_exp_f32_e32 v203, v136
	s_waitcnt lgkmcnt(8)
	v_mfma_f32_32x32x16_bf16 v[64:79], v[214:217], v[116:119], v[64:79]
	v_add_f32_e32 v134, v180, v134
	v_exp_f32_e32 v204, v137
	v_add_f32_e32 v134, v181, v134
	v_add_f32_e32 v134, v206, v134
	v_add_f32_e32 v134, v202, v134
	v_add_f32_e32 v134, v203, v134
	v_add_f32_e32 v134, v204, v134
	s_waitcnt lgkmcnt(7)
	v_mfma_f32_32x32x16_bf16 v[80:95], v[218:221], v[108:111], v[80:95]
	v_add_f32_e32 v134, v205, v134
	v_exp_f32_e32 v210, v147
	v_add_f32_e32 v134, v207, v134
	v_exp_f32_e32 v211, v144
	v_add_f32_e32 v134, v148, v134
	v_exp_f32_e32 v212, v145
	v_add_f32_e32 v134, v149, v134
	s_waitcnt lgkmcnt(6)
	v_mfma_f32_32x32x16_bf16 v[64:79], v[222:225], v[108:111], v[64:79]
	v_add_f32_e32 v134, v209, v134
	v_add_f32_e32 v134, v210, v134
	v_add_f32_e32 v134, v211, v134
	v_add_f32_e32 v176, v212, v134
	v_cvt_pk_bf16_f32 v134, v190, v191
	v_cvt_pk_bf16_f32 v136, v194, v196
	s_waitcnt lgkmcnt(5)
	v_mfma_f32_32x32x16_bf16 v[80:95], v[226:229], v[104:107], v[80:95]
	v_cvt_pk_bf16_f32 v137, v195, v197
	v_cvt_pk_bf16_f32 v139, v184, v186
	v_cvt_pk_bf16_f32 v142, v142, v143
	s_waitcnt lgkmcnt(4)
	v_mfma_f32_32x32x16_bf16 v[64:79], v[230:233], v[104:107], v[64:79]
	v_cvt_pk_bf16_f32 v143, v180, v181
	v_cvt_pk_bf16_f32 v144, v206, v202
	v_cvt_pk_bf16_f32 v145, v203, v204
	v_cvt_pk_bf16_f32 v146, v205, v207
	v_cvt_pk_bf16_f32 v147, v148, v149
	v_cvt_pk_bf16_f32 v148, v209, v210
	v_cvt_pk_bf16_f32 v149, v211, v212
	s_waitcnt lgkmcnt(3)
	v_mfma_f32_32x32x16_bf16 v[80:95], v[234:237], v[100:103], v[80:95]
	s_waitcnt lgkmcnt(2)
	v_mfma_f32_32x32x16_bf16 v[64:79], v[238:241], v[100:103], v[64:79]
	s_waitcnt lgkmcnt(1)
	v_mfma_f32_32x32x16_bf16 v[80:95], v[198:201], v[96:99], v[80:95]
	s_waitcnt lgkmcnt(0)
	v_mfma_f32_32x32x16_bf16 v[64:79], v[242:245], v[96:99], v[64:79]
	global_load_dwordx4 v[218:221], v132, s[28:29]
	global_load_dwordx4 v[222:225], v133, s[28:29]
	global_load_dwordx4 v[226:229], v132, s[30:31]
	global_load_dwordx4 v[230:233], v133, s[30:31]
	s_add_u32 s28, s28, 0x8000
	s_addc_u32 s29, s29, 0
	s_add_u32 s30, s30, 0x8000
	s_addc_u32 s31, s31, 0
	ds_read_b64_tr_b16 v[196:197], v161 offset:0
	ds_read_b64_tr_b16 v[198:199], v161 offset:0x800
	ds_read_b64_tr_b16 v[200:201], v161 offset:0x1000
	ds_read_b64_tr_b16 v[202:203], v161 offset:0x1800
	ds_read_b64_tr_b16 v[204:205], v161 offset:0x2000
	ds_read_b64_tr_b16 v[206:207], v161 offset:0x2800
	ds_read_b64_tr_b16 v[210:211], v161 offset:0x3000
	ds_read_b64_tr_b16 v[212:213], v161 offset:0x3800
	s_waitcnt lgkmcnt(0)
	s_nop 0
	v_mfma_f32_32x32x16_bf16 v[0:15], v[134:137], v[196:199], v[0:15]
	ds_read_b64_tr_b16 v[196:197], v161 offset:0x200
	ds_read_b64_tr_b16 v[198:199], v161 offset:0xa00
	v_max_f32_e32 v234, v80, v81
	v_max3_f32 v234, v234, v82, v83
	v_max3_f32 v234, v234, v84, v85
	v_max3_f32 v234, v234, v86, v87
	v_max3_f32 v234, v234, v88, v89
	v_mfma_f32_32x32x16_bf16 v[0:15], v[138:141], v[200:203], v[0:15]
	ds_read_b64_tr_b16 v[200:201], v161 offset:0x1200
	ds_read_b64_tr_b16 v[202:203], v161 offset:0x1a00
	v_max3_f32 v234, v234, v90, v91
	v_max3_f32 v234, v234, v92, v93
	v_max3_f32 v234, v234, v94, v95
	v_max3_f32 v234, v234, v64, v65
	v_max3_f32 v234, v234, v66, v67
	v_mfma_f32_32x32x16_bf16 v[0:15], v[142:145], v[204:207], v[0:15]
	ds_read_b64_tr_b16 v[204:205], v161 offset:0x2200
	ds_read_b64_tr_b16 v[206:207], v161 offset:0x2a00
	ds_read_b64_tr_b16 v[214:215], v161 offset:0x3200
	ds_read_b64_tr_b16 v[216:217], v161 offset:0x3a00
	v_max3_f32 v234, v234, v68, v69
	v_max3_f32 v234, v234, v70, v71
	v_max3_f32 v234, v234, v72, v73
	v_max3_f32 v234, v234, v74, v75
	v_max3_f32 v234, v234, v76, v77
	s_waitcnt lgkmcnt(0)
	v_mfma_f32_32x32x16_bf16 v[0:15], v[146:149], v[210:213], v[0:15]
	v_max3_f32 v234, v234, v78, v79
	v_mov_b32_e32 v235, v234
	v_mfma_f32_32x32x16_bf16 v[48:63], v[134:137], v[196:199], v[48:63]
	ds_read_b64_tr_b16 v[196:197], v161 offset:0x400
	ds_read_b64_tr_b16 v[198:199], v161 offset:0xc00
	v_permlane32_swap_b32_e32 v234, v235
	v_max_f32_e32 v234, v234, v235
	v_mfma_f32_32x32x16_bf16 v[48:63], v[138:141], v[200:203], v[48:63]
	ds_read_b64_tr_b16 v[200:201], v161 offset:0x1400
	ds_read_b64_tr_b16 v[202:203], v161 offset:0x1c00
	v_sub_f32_e32 v235, v234, v175
	v_max_f32_e32 v234, v175, v234
	v_sub_f32_e32 v236, v175, v234
	v_mul_f32_e32 v236, 0x3e0293ee, v236
	v_mfma_f32_32x32x16_bf16 v[48:63], v[142:145], v[204:207], v[48:63]
	ds_read_b64_tr_b16 v[204:205], v161 offset:0x2400
	ds_read_b64_tr_b16 v[206:207], v161 offset:0x2c00
	ds_read_b64_tr_b16 v[210:211], v161 offset:0x3400
	ds_read_b64_tr_b16 v[212:213], v161 offset:0x3c00
	v_exp_f32_e32 v236, v236
	v_cmp_ge_f32_e32 vcc, s15, v235
	s_cmp_eq_u64 vcc, exec
	s_cselect_b64 s[8:9], -1, 0
	s_waitcnt lgkmcnt(0)
	v_mfma_f32_32x32x16_bf16 v[48:63], v[146:149], v[214:217], v[48:63]
	v_cndmask_b32_e64 v179, v236, 1.0, s[8:9]
	v_cndmask_b32_e64 v234, v234, v175, s[8:9]
	v_mul_f32_e32 v238, 0xbe0293ee, v234
	v_pk_fma_f32 v[88:89], v[88:89], s[14:15], v[238:239] op_sel_hi:[1,0,0]
	v_pk_fma_f32 v[80:81], v[80:81], s[14:15], v[238:239] op_sel_hi:[1,0,0]
	v_mfma_f32_32x32x16_bf16 v[32:47], v[134:137], v[196:199], v[32:47]
	ds_read_b64_tr_b16 v[196:197], v161 offset:0x600
	ds_read_b64_tr_b16 v[198:199], v161 offset:0xe00
	v_pk_fma_f32 v[82:83], v[82:83], s[14:15], v[238:239] op_sel_hi:[1,0,0]
	v_pk_fma_f32 v[84:85], v[84:85], s[14:15], v[238:239] op_sel_hi:[1,0,0]
	v_pk_fma_f32 v[86:87], v[86:87], s[14:15], v[238:239] op_sel_hi:[1,0,0]
	v_pk_fma_f32 v[90:91], v[90:91], s[14:15], v[238:239] op_sel_hi:[1,0,0]
	v_mfma_f32_32x32x16_bf16 v[32:47], v[138:141], v[200:203], v[32:47]
	ds_read_b64_tr_b16 v[200:201], v161 offset:0x1600
	ds_read_b64_tr_b16 v[202:203], v161 offset:0x1e00
	v_pk_fma_f32 v[92:93], v[92:93], s[14:15], v[238:239] op_sel_hi:[1,0,0]
	v_pk_fma_f32 v[94:95], v[94:95], s[14:15], v[238:239] op_sel_hi:[1,0,0]
	v_pk_fma_f32 v[188:189], v[64:65], s[14:15], v[238:239] op_sel_hi:[1,0,0]
	v_pk_fma_f32 v[190:191], v[66:67], s[14:15], v[238:239] op_sel_hi:[1,0,0]
	v_mfma_f32_32x32x16_bf16 v[32:47], v[142:145], v[204:207], v[32:47]
	ds_read_b64_tr_b16 v[204:205], v161 offset:0x2600
	ds_read_b64_tr_b16 v[206:207], v161 offset:0x2e00
	ds_read_b64_tr_b16 v[214:215], v161 offset:0x3600
	ds_read_b64_tr_b16 v[216:217], v161 offset:0x3e00
	v_pk_fma_f32 v[182:183], v[70:71], s[14:15], v[238:239] op_sel_hi:[1,0,0]
	v_pk_fma_f32 v[184:185], v[72:73], s[14:15], v[238:239] op_sel_hi:[1,0,0]
	v_pk_fma_f32 v[186:187], v[74:75], s[14:15], v[238:239] op_sel_hi:[1,0,0]
	s_waitcnt lgkmcnt(0)
	v_mfma_f32_32x32x16_bf16 v[32:47], v[146:149], v[210:213], v[32:47]
	v_fmamk_f32 v192, v68, 0x3e0293ee, v238
	v_fmamk_f32 v181, v69, 0x3e0293ee, v238
	v_fmamk_f32 v180, v76, 0x3e0293ee, v238
	v_mfma_f32_32x32x16_bf16 v[16:31], v[134:137], v[196:199], v[16:31]
	v_fmamk_f32 v193, v77, 0x3e0293ee, v238
	v_fmamk_f32 v194, v78, 0x3e0293ee, v238
	v_fmamk_f32 v177, v79, 0x3e0293ee, v238
	v_mov_b32_e32 v134, v234
	v_exp_f32_e32 v135, v88
	v_exp_f32_e32 v136, v89
	v_exp_f32_e32 v137, v90
	v_mfma_f32_32x32x16_bf16 v[16:31], v[138:141], v[200:203], v[16:31]
	v_exp_f32_e32 v139, v91
	v_exp_f32_e32 v138, v92
	v_exp_f32_e32 v140, v93
	v_exp_f32_e32 v141, v94
	v_mfma_f32_32x32x16_bf16 v[16:31], v[142:145], v[204:207], v[16:31]
	v_exp_f32_e32 v142, v95
	v_exp_f32_e32 v143, v80
	v_exp_f32_e32 v144, v81
	v_exp_f32_e32 v145, v82
	v_mfma_f32_32x32x16_bf16 v[16:31], v[146:149], v[214:217], v[16:31]
	v_exp_f32_e32 v146, v83
	v_exp_f32_e32 v147, v84
	v_exp_f32_e32 v149, v85
	v_exp_f32_e32 v148, v86
	v_exp_f32_e32 v175, v87
	v_cmp_gt_f32_e32 vcc, 1.0, v179
	s_waitcnt vmcnt(0)
	ds_write_b128 v162, v[226:229] offset:32768
	ds_write_b128 v163, v[230:233] offset:32768
	s_barrier
	s_waitcnt vmcnt(0)
	ds_write_b128 v164, v[218:221]
	ds_write_b128 v165, v[222:225]
	s_cbranch_vccz .LBB0_437
	s_and_saveexec_b64 s[2:3], s[6:7]
	ds_write_b32 v158, v179 offset:128
	s_or_b64 exec, exec, s[2:3]
	s_waitcnt lgkmcnt(0)
	v_add_u32_e32 v234, v131, v128
	ds_read_b128 v[218:221], v234 offset:224
	ds_read_b128 v[222:225], v234 offset:192
	ds_read_b128 v[226:229], v234 offset:160
	ds_read_b128 v[230:233], v234 offset:128
	s_waitcnt lgkmcnt(3)
	v_pk_mul_f32 v[12:13], v[12:13], v[218:219]
	s_waitcnt lgkmcnt(2)
	v_pk_mul_f32 v[8:9], v[8:9], v[222:223]
	s_waitcnt lgkmcnt(1)
	v_pk_mul_f32 v[4:5], v[4:5], v[226:227]
	v_pk_mul_f32 v[14:15], v[14:15], v[220:221]
	v_pk_mul_f32 v[10:11], v[10:11], v[224:225]
	v_pk_mul_f32 v[6:7], v[6:7], v[228:229]
	s_waitcnt lgkmcnt(0)
	v_pk_mul_f32 v[2:3], v[2:3], v[232:233]
	v_pk_mul_f32 v[0:1], v[0:1], v[230:231]
	v_pk_mul_f32 v[60:61], v[60:61], v[218:219]
	v_pk_mul_f32 v[56:57], v[56:57], v[222:223]
	v_pk_mul_f32 v[52:53], v[52:53], v[226:227]
	v_pk_mul_f32 v[62:63], v[62:63], v[220:221]
	v_pk_mul_f32 v[58:59], v[58:59], v[224:225]
	v_pk_mul_f32 v[54:55], v[54:55], v[228:229]
	v_pk_mul_f32 v[50:51], v[50:51], v[232:233]
	v_pk_mul_f32 v[48:49], v[48:49], v[230:231]
	v_pk_mul_f32 v[44:45], v[44:45], v[218:219]
	v_pk_mul_f32 v[40:41], v[40:41], v[222:223]
	v_pk_mul_f32 v[36:37], v[36:37], v[226:227]
	v_pk_mul_f32 v[46:47], v[46:47], v[220:221]
	v_pk_mul_f32 v[42:43], v[42:43], v[224:225]
	v_pk_mul_f32 v[38:39], v[38:39], v[228:229]
	v_pk_mul_f32 v[34:35], v[34:35], v[232:233]
	v_pk_mul_f32 v[32:33], v[32:33], v[230:231]
	v_pk_mul_f32 v[28:29], v[28:29], v[218:219]
	v_pk_mul_f32 v[24:25], v[24:25], v[222:223]
	v_pk_mul_f32 v[20:21], v[20:21], v[226:227]
	v_pk_mul_f32 v[30:31], v[30:31], v[220:221]
	v_pk_mul_f32 v[26:27], v[26:27], v[224:225]
	v_pk_mul_f32 v[22:23], v[22:23], v[228:229]
	v_pk_mul_f32 v[18:19], v[18:19], v[232:233]
	v_pk_mul_f32 v[16:17], v[16:17], v[230:231]
.LBB0_437:
	s_waitcnt lgkmcnt(0)
	s_barrier
	ds_read_b128 v[64:67], v166 offset:32768
	ds_read_b128 v[68:71], v166 offset:40960
	ds_read_b128 v[196:199], v167 offset:32768
	ds_read_b128 v[200:203], v167 offset:40960
	ds_read_b128 v[204:207], v168 offset:32768
	ds_read_b128 v[210:213], v168 offset:40960
	v_exp_f32_e32 v188, v188
	v_exp_f32_e32 v189, v189
	s_waitcnt lgkmcnt(5)
	v_mfma_f32_32x32x16_bf16 v[80:95], v[64:67], v[124:127], 0
	v_exp_f32_e32 v190, v190
	v_exp_f32_e32 v191, v191
	v_exp_f32_e32 v192, v192
	v_exp_f32_e32 v195, v181
	v_exp_f32_e32 v182, v182
	v_exp_f32_e32 v183, v183
	v_exp_f32_e32 v184, v184
	s_waitcnt lgkmcnt(4)
	v_mfma_f32_32x32x16_bf16 v[64:79], v[68:71], v[124:127], 0
	v_exp_f32_e32 v185, v185
	v_exp_f32_e32 v186, v186
	v_exp_f32_e32 v187, v187
	v_exp_f32_e32 v193, v193
	v_exp_f32_e32 v194, v194
	v_exp_f32_e32 v177, v177
	s_waitcnt lgkmcnt(3)
	v_mfma_f32_32x32x16_bf16 v[80:95], v[196:199], v[120:123], v[80:95]
	ds_read_b128 v[196:199], v169 offset:32768
	ds_read_b128 v[214:217], v169 offset:40960
	ds_read_b128 v[218:221], v170 offset:32768
	ds_read_b128 v[222:225], v170 offset:40960
	ds_read_b128 v[226:229], v171 offset:32768
	ds_read_b128 v[230:233], v171 offset:40960
	ds_read_b128 v[234:237], v172 offset:32768
	ds_read_b128 v[238:241], v172 offset:40960
	s_waitcnt lgkmcnt(10)
	v_mfma_f32_32x32x16_bf16 v[64:79], v[200:203], v[120:123], v[64:79]
	ds_read_b128 v[200:203], v173 offset:32768
	ds_read_b128 v[242:245], v173 offset:40960
	s_waitcnt lgkmcnt(11)
	v_mfma_f32_32x32x16_bf16 v[80:95], v[204:207], v[112:115], v[80:95]
	v_exp_f32_e32 v204, v180
	v_add_f32_e32 v180, v144, v143
	v_add_f32_e32 v180, v145, v180
	v_add_f32_e32 v180, v146, v180
	v_add_f32_e32 v180, v147, v180
	v_add_f32_e32 v180, v149, v180
	s_waitcnt lgkmcnt(10)
	v_mfma_f32_32x32x16_bf16 v[64:79], v[210:213], v[112:115], v[64:79]
	v_add_f32_e32 v180, v148, v180
	v_add_f32_e32 v180, v175, v180
	v_add_f32_e32 v180, v135, v180
	v_add_f32_e32 v180, v136, v180
	v_add_f32_e32 v180, v137, v180
	v_add_f32_e32 v180, v139, v180
	v_add_f32_e32 v180, v138, v180
	s_waitcnt lgkmcnt(9)
	v_mfma_f32_32x32x16_bf16 v[80:95], v[196:199], v[116:119], v[80:95]
	v_add_f32_e32 v180, v140, v180
	v_add_f32_e32 v180, v141, v180
	v_add_f32_e32 v180, v142, v180
	v_add_f32_e32 v180, v188, v180
	v_add_f32_e32 v180, v189, v180
	v_add_f32_e32 v180, v190, v180
	v_add_f32_e32 v180, v191, v180
	s_waitcnt lgkmcnt(8)
	v_mfma_f32_32x32x16_bf16 v[64:79], v[214:217], v[116:119], v[64:79]
	v_add_f32_e32 v180, v192, v180
	v_add_f32_e32 v180, v195, v180
	v_add_f32_e32 v180, v182, v180
	v_add_f32_e32 v180, v183, v180
	v_add_f32_e32 v180, v184, v180
	v_add_f32_e32 v180, v185, v180
	v_add_f32_e32 v180, v186, v180
	s_waitcnt lgkmcnt(7)
	v_mfma_f32_32x32x16_bf16 v[80:95], v[218:221], v[108:111], v[80:95]
	v_add_f32_e32 v180, v187, v180
	v_add_f32_e32 v180, v204, v180
	v_add_f32_e32 v180, v193, v180
	v_add_f32_e32 v180, v194, v180
	v_add_f32_e32 v180, v177, v180
	s_waitcnt lgkmcnt(6)
	v_mfma_f32_32x32x16_bf16 v[64:79], v[222:225], v[108:111], v[64:79]
	v_cvt_pk_bf16_f32 v144, v143, v144
	v_cvt_pk_bf16_f32 v145, v145, v146
	v_cvt_pk_bf16_f32 v146, v147, v149
	v_cvt_pk_bf16_f32 v147, v148, v175
	v_cvt_pk_bf16_f32 v136, v135, v136
	v_cvt_pk_bf16_f32 v137, v137, v139
	v_cvt_pk_bf16_f32 v138, v138, v140
	s_waitcnt lgkmcnt(5)
	v_mfma_f32_32x32x16_bf16 v[80:95], v[226:229], v[104:107], v[80:95]
	v_cvt_pk_bf16_f32 v139, v141, v142
	v_cvt_pk_bf16_f32 v140, v188, v189
	v_cvt_pk_bf16_f32 v141, v190, v191
	v_cvt_pk_bf16_f32 v142, v192, v195
	v_cvt_pk_bf16_f32 v143, v182, v183
	v_cvt_pk_bf16_f32 v182, v184, v185
	v_cvt_pk_bf16_f32 v183, v186, v187
	s_waitcnt lgkmcnt(4)
	v_mfma_f32_32x32x16_bf16 v[64:79], v[230:233], v[104:107], v[64:79]
	v_cvt_pk_bf16_f32 v184, v204, v193
	v_cvt_pk_bf16_f32 v185, v194, v177
	s_waitcnt lgkmcnt(3)
	v_mfma_f32_32x32x16_bf16 v[80:95], v[234:237], v[100:103], v[80:95]
	s_waitcnt lgkmcnt(2)
	v_mfma_f32_32x32x16_bf16 v[64:79], v[238:241], v[100:103], v[64:79]
	s_waitcnt lgkmcnt(1)
	v_mfma_f32_32x32x16_bf16 v[80:95], v[200:203], v[96:99], v[80:95]
	s_waitcnt lgkmcnt(0)
	v_mfma_f32_32x32x16_bf16 v[64:79], v[242:245], v[96:99], v[64:79]
	global_load_dwordx4 v[226:229], v132, s[28:29]
	global_load_dwordx4 v[230:233], v132, s[30:31]
	global_load_dwordx4 v[234:237], v133, s[28:29]
	global_load_dwordx4 v[238:241], v133, s[30:31]
	s_add_u32 s28, s28, 0x8000
	s_addc_u32 s29, s29, 0
	s_add_u32 s30, s30, 0x8000
	s_addc_u32 s31, s31, 0
	ds_read_b64_tr_b16 v[202:203], v160 offset:0
	ds_read_b64_tr_b16 v[204:205], v160 offset:0x800
	ds_read_b64_tr_b16 v[210:211], v160 offset:0x1000
	ds_read_b64_tr_b16 v[212:213], v160 offset:0x1800
	ds_read_b64_tr_b16 v[214:215], v160 offset:0x2000
	ds_read_b64_tr_b16 v[216:217], v160 offset:0x2800
	ds_read_b64_tr_b16 v[218:219], v160 offset:0x3000
	ds_read_b64_tr_b16 v[220:221], v160 offset:0x3800
	s_waitcnt lgkmcnt(0)
	s_nop 0
	v_mfma_f32_32x32x16_bf16 v[0:15], v[144:147], v[202:205], v[0:15]
	ds_read_b64_tr_b16 v[202:203], v160 offset:0x200
	ds_read_b64_tr_b16 v[204:205], v160 offset:0xa00
	v_max_f32_e32 v242, v80, v81
	v_max3_f32 v242, v242, v82, v83
	v_max3_f32 v242, v242, v84, v85
	v_max3_f32 v242, v242, v86, v87
	v_max3_f32 v242, v242, v88, v89
	v_mfma_f32_32x32x16_bf16 v[0:15], v[136:139], v[210:213], v[0:15]
	ds_read_b64_tr_b16 v[210:211], v160 offset:0x1200
	ds_read_b64_tr_b16 v[212:213], v160 offset:0x1a00
	v_max3_f32 v242, v242, v90, v91
	v_max3_f32 v242, v242, v92, v93
	v_max3_f32 v242, v242, v94, v95
	v_max3_f32 v242, v242, v64, v65
	v_max3_f32 v242, v242, v66, v67
	v_mfma_f32_32x32x16_bf16 v[0:15], v[140:143], v[214:217], v[0:15]
	ds_read_b64_tr_b16 v[214:215], v160 offset:0x2200
	ds_read_b64_tr_b16 v[216:217], v160 offset:0x2a00
	ds_read_b64_tr_b16 v[222:223], v160 offset:0x3200
	ds_read_b64_tr_b16 v[224:225], v160 offset:0x3a00
	v_max3_f32 v242, v242, v68, v69
	v_max3_f32 v242, v242, v70, v71
	v_max3_f32 v242, v242, v72, v73
	v_max3_f32 v242, v242, v74, v75
	v_max3_f32 v242, v242, v76, v77
	s_waitcnt lgkmcnt(0)
	v_mfma_f32_32x32x16_bf16 v[0:15], v[182:185], v[218:221], v[0:15]
	v_max3_f32 v242, v242, v78, v79
	v_mov_b32_e32 v243, v242
	v_mfma_f32_32x32x16_bf16 v[48:63], v[144:147], v[202:205], v[48:63]
	ds_read_b64_tr_b16 v[202:203], v160 offset:0x400
	ds_read_b64_tr_b16 v[204:205], v160 offset:0xc00
	v_permlane32_swap_b32_e32 v242, v243
	v_max_f32_e32 v242, v242, v243
	v_mfma_f32_32x32x16_bf16 v[48:63], v[136:139], v[210:213], v[48:63]
	ds_read_b64_tr_b16 v[210:211], v160 offset:0x1400
	ds_read_b64_tr_b16 v[212:213], v160 offset:0x1c00
	v_sub_f32_e32 v243, v242, v134
	v_max_f32_e32 v242, v134, v242
	v_sub_f32_e32 v148, v134, v242
	v_mul_f32_e32 v148, 0x3e0293ee, v148
	v_mfma_f32_32x32x16_bf16 v[48:63], v[140:143], v[214:217], v[48:63]
	ds_read_b64_tr_b16 v[214:215], v160 offset:0x2400
	ds_read_b64_tr_b16 v[216:217], v160 offset:0x2c00
	ds_read_b64_tr_b16 v[218:219], v160 offset:0x3400
	ds_read_b64_tr_b16 v[220:221], v160 offset:0x3c00
	v_exp_f32_e32 v148, v148
	v_cmp_ge_f32_e32 vcc, s15, v243
	s_cmp_eq_u64 vcc, exec
	s_cselect_b64 s[8:9], -1, 0
	s_waitcnt lgkmcnt(0)
	v_mfma_f32_32x32x16_bf16 v[48:63], v[182:185], v[222:225], v[48:63]
	v_cndmask_b32_e64 v177, v148, 1.0, s[8:9]
	v_cndmask_b32_e64 v175, v242, v134, s[8:9]
	v_mul_f32_e32 v244, 0xbe0293ee, v175
	v_pk_fma_f32 v[80:81], v[80:81], s[14:15], v[244:245] op_sel_hi:[1,0,0]
	v_pk_fma_f32 v[82:83], v[82:83], s[14:15], v[244:245] op_sel_hi:[1,0,0]
	v_mfma_f32_32x32x16_bf16 v[32:47], v[144:147], v[202:205], v[32:47]
	ds_read_b64_tr_b16 v[202:203], v160 offset:0x600
	ds_read_b64_tr_b16 v[204:205], v160 offset:0xe00
	v_pk_fma_f32 v[84:85], v[84:85], s[14:15], v[244:245] op_sel_hi:[1,0,0]
	v_pk_fma_f32 v[86:87], v[86:87], s[14:15], v[244:245] op_sel_hi:[1,0,0]
	v_pk_fma_f32 v[88:89], v[88:89], s[14:15], v[244:245] op_sel_hi:[1,0,0]
	v_pk_fma_f32 v[90:91], v[90:91], s[14:15], v[244:245] op_sel_hi:[1,0,0]
	v_mfma_f32_32x32x16_bf16 v[32:47], v[136:139], v[210:213], v[32:47]
	ds_read_b64_tr_b16 v[210:211], v160 offset:0x1600
	ds_read_b64_tr_b16 v[212:213], v160 offset:0x1e00
	v_pk_fma_f32 v[92:93], v[92:93], s[14:15], v[244:245] op_sel_hi:[1,0,0]
	v_pk_fma_f32 v[94:95], v[94:95], s[14:15], v[244:245] op_sel_hi:[1,0,0]
	v_pk_fma_f32 v[134:135], v[72:73], s[14:15], v[244:245] op_sel_hi:[1,0,0]
	v_pk_fma_f32 v[148:149], v[74:75], s[14:15], v[244:245] op_sel_hi:[1,0,0]
	v_mfma_f32_32x32x16_bf16 v[32:47], v[140:143], v[214:217], v[32:47]
	ds_read_b64_tr_b16 v[214:215], v160 offset:0x2600
	ds_read_b64_tr_b16 v[216:217], v160 offset:0x2e00
	ds_read_b64_tr_b16 v[222:223], v160 offset:0x3600
	ds_read_b64_tr_b16 v[224:225], v160 offset:0x3e00
	v_exp_f32_e32 v190, v80
	v_exp_f32_e32 v191, v81
	v_exp_f32_e32 v192, v82
	s_waitcnt lgkmcnt(0)
	v_mfma_f32_32x32x16_bf16 v[32:47], v[182:185], v[218:221], v[32:47]
	v_exp_f32_e32 v193, v83
	v_exp_f32_e32 v194, v84
	v_exp_f32_e32 v196, v85
	v_mfma_f32_32x32x16_bf16 v[16:31], v[144:147], v[202:205], v[16:31]
	v_pk_fma_f32 v[144:145], v[78:79], s[14:15], v[244:245] op_sel_hi:[1,0,0]
	v_pk_fma_f32 v[146:147], v[76:77], s[14:15], v[244:245] op_sel_hi:[1,0,0]
	v_exp_f32_e32 v195, v86
	v_exp_f32_e32 v197, v87
	v_mfma_f32_32x32x16_bf16 v[16:31], v[136:139], v[210:213], v[16:31]
	v_pk_fma_f32 v[136:137], v[70:71], s[14:15], v[244:245] op_sel_hi:[1,0,0]
	v_pk_fma_f32 v[138:139], v[68:69], s[14:15], v[244:245] op_sel_hi:[1,0,0]
	v_exp_f32_e32 v186, v91
	v_exp_f32_e32 v187, v93
	v_mfma_f32_32x32x16_bf16 v[16:31], v[140:143], v[214:217], v[16:31]
	v_pk_fma_f32 v[140:141], v[66:67], s[14:15], v[244:245] op_sel_hi:[1,0,0]
	v_pk_fma_f32 v[142:143], v[64:65], s[14:15], v[244:245] op_sel_hi:[1,0,0]
	v_exp_f32_e32 v188, v94
	v_exp_f32_e32 v189, v95
	v_mfma_f32_32x32x16_bf16 v[16:31], v[182:185], v[222:225], v[16:31]
	v_exp_f32_e32 v182, v88
	v_exp_f32_e32 v183, v89
	v_exp_f32_e32 v184, v90
	v_exp_f32_e32 v185, v92
	v_cmp_gt_f32_e32 vcc, 1.0, v177
	s_waitcnt vmcnt(0)
	ds_write_b128 v162, v[230:233] offset:49152
	ds_write_b128 v163, v[238:241] offset:49152
	s_barrier
	s_waitcnt vmcnt(0)
	ds_write_b128 v164, v[226:229] offset:16384
	ds_write_b128 v165, v[234:237] offset:16384
	s_cbranch_vccz .LBB0_441
	s_and_saveexec_b64 s[2:3], s[6:7]
	ds_write_b32 v158, v177 offset:128
	s_or_b64 exec, exec, s[2:3]
	s_waitcnt lgkmcnt(0)
	v_add_u32_e32 v242, v131, v128
	ds_read_b128 v[226:229], v242 offset:224
	ds_read_b128 v[230:233], v242 offset:192
	ds_read_b128 v[234:237], v242 offset:160
	ds_read_b128 v[238:241], v242 offset:128
	s_waitcnt lgkmcnt(3)
	v_pk_mul_f32 v[12:13], v[12:13], v[226:227]
	s_waitcnt lgkmcnt(2)
	v_pk_mul_f32 v[8:9], v[8:9], v[230:231]
	s_waitcnt lgkmcnt(1)
	v_pk_mul_f32 v[4:5], v[4:5], v[234:235]
	v_pk_mul_f32 v[14:15], v[14:15], v[228:229]
	v_pk_mul_f32 v[10:11], v[10:11], v[232:233]
	v_pk_mul_f32 v[6:7], v[6:7], v[236:237]
	s_waitcnt lgkmcnt(0)
	v_pk_mul_f32 v[2:3], v[2:3], v[240:241]
	v_pk_mul_f32 v[0:1], v[0:1], v[238:239]
	v_pk_mul_f32 v[60:61], v[60:61], v[226:227]
	v_pk_mul_f32 v[56:57], v[56:57], v[230:231]
	v_pk_mul_f32 v[52:53], v[52:53], v[234:235]
	v_pk_mul_f32 v[62:63], v[62:63], v[228:229]
	v_pk_mul_f32 v[58:59], v[58:59], v[232:233]
	v_pk_mul_f32 v[54:55], v[54:55], v[236:237]
	v_pk_mul_f32 v[50:51], v[50:51], v[240:241]
	v_pk_mul_f32 v[48:49], v[48:49], v[238:239]
	v_pk_mul_f32 v[44:45], v[44:45], v[226:227]
	v_pk_mul_f32 v[40:41], v[40:41], v[230:231]
	v_pk_mul_f32 v[36:37], v[36:37], v[234:235]
	v_pk_mul_f32 v[46:47], v[46:47], v[228:229]
	v_pk_mul_f32 v[42:43], v[42:43], v[232:233]
	v_pk_mul_f32 v[38:39], v[38:39], v[236:237]
	v_pk_mul_f32 v[34:35], v[34:35], v[240:241]
	v_pk_mul_f32 v[32:33], v[32:33], v[238:239]
	v_pk_mul_f32 v[28:29], v[28:29], v[226:227]
	v_pk_mul_f32 v[24:25], v[24:25], v[230:231]
	v_pk_mul_f32 v[20:21], v[20:21], v[234:235]
	v_pk_mul_f32 v[30:31], v[30:31], v[228:229]
	v_pk_mul_f32 v[26:27], v[26:27], v[232:233]
	v_pk_mul_f32 v[22:23], v[22:23], v[236:237]
	v_pk_mul_f32 v[18:19], v[18:19], v[240:241]
	v_pk_mul_f32 v[16:17], v[16:17], v[238:239]
